# v11 plus the eight LayerNorm row-statistic slot loads issued together (one wait)
# speedup vs baseline: 1.0060x; 1.0019x over previous
;     __device__ __forceinline__ void fused(f32x4 (&acc)[2][2][4][2], const pg8::Unit& u, int wr, int wc, LAS unsigned char* lds) const {
;     ...
;         if (t2 < 256) { const int r = t2; const unsigned long long* sl_ = stats + (size_t)(u.pm * 256 + r) * 8; float a = 0.f, q = 0.f;
; #pragma unroll
;             for (int k = 0; k < 8; ++k) { const unsigned long long w = __hip_atomic_load(sl_ + k, __ATOMIC_RELAXED, __HIP_MEMORY_SCOPE_AGENT); a += __uint_as_float((unsigned)w); q += __uint_as_float((unsigned)(w >> 32)); }
;             const float mean = a * (1.f / DM), var = q * (1.f / DM) - mean * mean; tab[r * 2] = mean; tab[r * 2 + 1] = 1.f / sqrtf(fmaxf(var, 0.f) + 1e-5f); }
.LBB0_751:
	s_waitcnt lgkmcnt(0)
	s_barrier
	s_and_saveexec_b64 s[6:7], s[42:43]
	s_cbranch_execz .LBB0_753
	v_lshlrev_b64 v[0:1], 6, v[0:1]
	v_lshl_add_u64 v[0:1], s[58:59], 0, v[0:1]
	flat_load_dwordx2 v[2:3], v[0:1] sc1
	flat_load_dwordx2 v[4:5], v[0:1] offset:8 sc1
	flat_load_dwordx2 v[6:7], v[0:1] offset:16 sc1
	flat_load_dwordx2 v[8:9], v[0:1] offset:24 sc1
	flat_load_dwordx2 v[10:11], v[0:1] offset:32 sc1
	flat_load_dwordx2 v[12:13], v[0:1] offset:40 sc1
	flat_load_dwordx2 v[14:15], v[0:1] offset:48 sc1
	flat_load_dwordx2 v[16:17], v[0:1] offset:56 sc1
	s_mov_b32 s4, 0x3a000000
	s_waitcnt vmcnt(0) lgkmcnt(0)
	v_add_f32_e32 v18, 0, v2
	v_add_f32_e32 v19, 0, v3
	v_add_f32_e32 v18, v18, v4
	v_add_f32_e32 v19, v19, v5
	v_add_f32_e32 v18, v18, v6
	v_add_f32_e32 v19, v19, v7
	v_add_f32_e32 v18, v18, v8
	v_add_f32_e32 v19, v19, v9
	v_add_f32_e32 v18, v18, v10
	v_add_f32_e32 v19, v19, v11
	v_add_f32_e32 v18, v18, v12
	v_add_f32_e32 v19, v19, v13
	v_add_f32_e32 v18, v18, v14
	v_add_f32_e32 v19, v19, v15
	v_add_f32_e32 v0, v18, v16
	v_mul_f32_e32 v0, 0x3a000000, v0
	v_add_f32_e32 v1, v19, v17
	v_mul_f32_e32 v2, v0, v0
	v_fma_f32 v1, v1, s4, -v2
	v_max_f32_e32 v1, 0, v1
	v_add_f32_e32 v1, 0x3727c5ac, v1
	s_mov_b32 s4, 0xf800000
	v_cmp_gt_f32_e32 vcc, s4, v1
	v_mul_f32_e32 v3, 0x4f800000, v1
	v_lshl_add_u32 v2, v186, 3, 0
	v_cndmask_b32_e32 v1, v1, v3, vcc
	v_sqrt_f32_e32 v3, v1
	v_add_u32_e32 v2, 0x22080, v2
	v_add_u32_e32 v4, -1, v3
	v_fma_f32 v5, -v4, v3, v1
	v_cmp_ge_f32_e64 s[42:43], 0, v5
	v_add_u32_e32 v5, 1, v3
	s_nop 0
	v_cndmask_b32_e64 v4, v3, v4, s[42:43]
	v_fma_f32 v3, -v5, v3, v1
	v_cmp_lt_f32_e64 s[42:43], 0, v3
	s_nop 1
	v_cndmask_b32_e64 v3, v4, v5, s[42:43]
	v_mul_f32_e32 v4, 0x37800000, v3
	v_cndmask_b32_e32 v3, v3, v4, vcc
	v_cmp_class_f32_e32 vcc, v1, v203
	s_nop 1
	v_cndmask_b32_e32 v1, v3, v1, vcc
	v_div_scale_f32 v3, s[14:15], v1, v1, 1.0
	v_rcp_f32_e32 v4, v3
	s_nop 0
	v_fma_f32 v5, -v3, v4, 1.0
	v_fmac_f32_e32 v4, v5, v4
	v_div_scale_f32 v5, vcc, 1.0, v1, 1.0
	v_mul_f32_e32 v6, v5, v4
	v_fma_f32 v7, -v3, v6, v5
	v_fmac_f32_e32 v6, v7, v4
	v_fma_f32 v3, -v3, v6, v5
	v_div_fmas_f32 v3, v3, v4, v6
	v_div_fixup_f32 v1, v3, v1, 1.0
	ds_write_b64 v2, v[0:1]
